# nt (streaming) hint on the read-once f32 weight loads of P0 (adaLN GEMV and weight transposes), on top of sc1 write-through outputs and epilogue rewrites
# speedup vs baseline: 1.0023x; 1.0023x over previous
.LBB0_42:
	global_load_dwordx4 v[16:19], v[22:23], off nt
	v_lshl_add_u64 v[24:25], v[22:23], 0, s[8:9]
	s_add_i32 s23, s19, s22
	v_lshl_add_u64 v[54:55], v[24:25], 0, s[8:9]
	v_mov_b32_e32 v98, s23
	global_load_dwordx4 v[30:33], v[24:25], off nt
	global_load_dwordx4 v[34:37], v[54:55], off nt
	v_lshl_add_u64 v[24:25], v[54:55], 0, s[8:9]
	ds_read_b128 v[38:41], v98
	ds_read_b128 v[42:45], v98 offset:16
	ds_read_b128 v[46:49], v98 offset:32
	ds_read_b128 v[50:53], v98 offset:48
	ds_read_b128 v[54:57], v98 offset:64
	ds_read_b128 v[58:61], v98 offset:80
	ds_read_b128 v[62:65], v98 offset:96
	ds_read_b128 v[66:69], v98 offset:112
	ds_read_b128 v[70:73], v98 offset:128
	ds_read_b128 v[74:77], v98 offset:144
	ds_read_b128 v[78:81], v98 offset:160
	ds_read_b128 v[82:85], v98 offset:176
	ds_read_b128 v[86:89], v98 offset:192
	ds_read_b128 v[90:93], v98 offset:208
	ds_read_b128 v[94:97], v98 offset:224
	ds_read_b128 v[98:101], v98 offset:240
	global_load_dwordx4 v[102:105], v[24:25], off nt
	v_lshl_add_u64 v[24:25], v[24:25], 0, s[8:9]
	global_load_dwordx4 v[106:109], v[24:25], off nt
	v_lshl_add_u64 v[24:25], v[24:25], 0, s[8:9]
	global_load_dwordx4 v[110:113], v[24:25], off nt
	v_lshl_add_u64 v[24:25], v[24:25], 0, s[8:9]
	global_load_dwordx4 v[114:117], v[24:25], off nt
	v_lshl_add_u64 v[24:25], v[24:25], 0, s[8:9]
	global_load_dwordx4 v[118:121], v[24:25], off nt
	v_lshl_add_u64 v[24:25], v[24:25], 0, s[8:9]
	global_load_dwordx4 v[122:125], v[24:25], off nt
	v_lshl_add_u64 v[24:25], v[24:25], 0, s[8:9]
	v_lshl_add_u64 v[134:135], v[24:25], 0, s[8:9]
	global_load_dwordx4 v[126:129], v[24:25], off nt
	global_load_dwordx4 v[130:133], v[134:135], off nt
	v_lshl_add_u64 v[24:25], v[134:135], 0, s[8:9]
	global_load_dwordx4 v[134:137], v[24:25], off nt
	v_lshl_add_u64 v[24:25], v[24:25], 0, s[8:9]
	global_load_dwordx4 v[138:141], v[24:25], off nt
	v_lshl_add_u64 v[24:25], v[24:25], 0, s[8:9]
	global_load_dwordx4 v[142:145], v[24:25], off nt
	v_lshl_add_u64 v[24:25], v[24:25], 0, s[8:9]
	global_load_dwordx4 v[146:149], v[24:25], off nt
	v_lshl_add_u64 v[24:25], v[24:25], 0, s[8:9]
	global_load_dwordx4 v[150:153], v[24:25], off nt
	s_waitcnt lgkmcnt(14)
	v_mov_b32_e32 v154, v41
	v_mov_b32_e32 v156, v45
	s_waitcnt lgkmcnt(13)
	v_mov_b32_e32 v158, v49
	s_waitcnt lgkmcnt(12)
	v_mov_b32_e32 v160, v53
	s_waitcnt lgkmcnt(11)
	v_mov_b32_e32 v162, v57
	s_waitcnt lgkmcnt(10)
	v_mov_b32_e32 v164, v61
	s_waitcnt lgkmcnt(9)
	v_mov_b32_e32 v166, v65
	s_waitcnt lgkmcnt(8)
	v_mov_b32_e32 v168, v69
	s_waitcnt lgkmcnt(7)
	v_mov_b32_e32 v170, v73
	s_waitcnt lgkmcnt(6)
	v_mov_b32_e32 v172, v77
	s_waitcnt lgkmcnt(5)
	v_mov_b32_e32 v174, v81
	s_waitcnt lgkmcnt(4)
	v_mov_b32_e32 v176, v85
	s_waitcnt lgkmcnt(3)
	v_mov_b32_e32 v178, v89
	s_waitcnt lgkmcnt(2)
	v_mov_b32_e32 v180, v93
	s_waitcnt lgkmcnt(1)
	v_mov_b32_e32 v182, v97
	s_addk_i32 s22, 0x100
	s_waitcnt lgkmcnt(0)
	v_mov_b32_e32 v184, v101
	v_lshl_add_u64 v[22:23], v[22:23], 0, s[14:15]
	s_cmpk_eq_i32 s22, 0x1000
	s_waitcnt vmcnt(15)
	v_pk_fma_f32 v[2:3], v[18:19], v[38:39], v[2:3] op_sel_hi:[1,0,1]
	v_pk_fma_f32 v[0:1], v[16:17], v[38:39], v[0:1] op_sel_hi:[1,0,1]
	v_pk_fma_f32 v[6:7], v[18:19], v[38:39], v[6:7] op_sel:[0,1,0]
	v_pk_fma_f32 v[4:5], v[16:17], v[38:39], v[4:5] op_sel:[0,1,0]
	v_pk_fma_f32 v[10:11], v[18:19], v[40:41], v[10:11] op_sel_hi:[1,0,1]
	v_pk_fma_f32 v[8:9], v[16:17], v[40:41], v[8:9] op_sel_hi:[1,0,1]
	v_pk_fma_f32 v[14:15], v[18:19], v[154:155], v[14:15] op_sel_hi:[1,0,1]
	v_pk_fma_f32 v[12:13], v[16:17], v[154:155], v[12:13] op_sel_hi:[1,0,1]
	s_waitcnt vmcnt(14)
	v_pk_fma_f32 v[2:3], v[32:33], v[42:43], v[2:3] op_sel_hi:[1,0,1]
	v_pk_fma_f32 v[0:1], v[30:31], v[42:43], v[0:1] op_sel_hi:[1,0,1]
	v_pk_fma_f32 v[6:7], v[32:33], v[42:43], v[6:7] op_sel:[0,1,0]
	v_pk_fma_f32 v[4:5], v[30:31], v[42:43], v[4:5] op_sel:[0,1,0]
	v_pk_fma_f32 v[10:11], v[32:33], v[44:45], v[10:11] op_sel_hi:[1,0,1]
	v_pk_fma_f32 v[8:9], v[30:31], v[44:45], v[8:9] op_sel_hi:[1,0,1]
	v_pk_fma_f32 v[14:15], v[32:33], v[156:157], v[14:15] op_sel_hi:[1,0,1]
	v_pk_fma_f32 v[12:13], v[30:31], v[156:157], v[12:13] op_sel_hi:[1,0,1]
	s_waitcnt vmcnt(13)
	v_pk_fma_f32 v[2:3], v[36:37], v[46:47], v[2:3] op_sel_hi:[1,0,1]
	v_pk_fma_f32 v[0:1], v[34:35], v[46:47], v[0:1] op_sel_hi:[1,0,1]
	v_pk_fma_f32 v[6:7], v[36:37], v[46:47], v[6:7] op_sel:[0,1,0]
	v_pk_fma_f32 v[4:5], v[34:35], v[46:47], v[4:5] op_sel:[0,1,0]
	v_pk_fma_f32 v[10:11], v[36:37], v[48:49], v[10:11] op_sel_hi:[1,0,1]
	v_pk_fma_f32 v[8:9], v[34:35], v[48:49], v[8:9] op_sel_hi:[1,0,1]
	v_pk_fma_f32 v[14:15], v[36:37], v[158:159], v[14:15] op_sel_hi:[1,0,1]
	v_pk_fma_f32 v[12:13], v[34:35], v[158:159], v[12:13] op_sel_hi:[1,0,1]
	s_waitcnt vmcnt(12)
	v_pk_fma_f32 v[2:3], v[104:105], v[50:51], v[2:3] op_sel_hi:[1,0,1]
	v_pk_fma_f32 v[0:1], v[102:103], v[50:51], v[0:1] op_sel_hi:[1,0,1]
	v_pk_fma_f32 v[6:7], v[104:105], v[50:51], v[6:7] op_sel:[0,1,0]
	v_pk_fma_f32 v[4:5], v[102:103], v[50:51], v[4:5] op_sel:[0,1,0]
	v_pk_fma_f32 v[10:11], v[104:105], v[52:53], v[10:11] op_sel_hi:[1,0,1]
	v_pk_fma_f32 v[8:9], v[102:103], v[52:53], v[8:9] op_sel_hi:[1,0,1]
	v_pk_fma_f32 v[14:15], v[104:105], v[160:161], v[14:15] op_sel_hi:[1,0,1]
	v_pk_fma_f32 v[12:13], v[102:103], v[160:161], v[12:13] op_sel_hi:[1,0,1]
	s_waitcnt vmcnt(11)
	v_pk_fma_f32 v[2:3], v[108:109], v[54:55], v[2:3] op_sel_hi:[1,0,1]
	v_pk_fma_f32 v[0:1], v[106:107], v[54:55], v[0:1] op_sel_hi:[1,0,1]
	v_pk_fma_f32 v[6:7], v[108:109], v[54:55], v[6:7] op_sel:[0,1,0]
	v_pk_fma_f32 v[4:5], v[106:107], v[54:55], v[4:5] op_sel:[0,1,0]
	v_pk_fma_f32 v[10:11], v[108:109], v[56:57], v[10:11] op_sel_hi:[1,0,1]
	v_pk_fma_f32 v[8:9], v[106:107], v[56:57], v[8:9] op_sel_hi:[1,0,1]
	v_pk_fma_f32 v[14:15], v[108:109], v[162:163], v[14:15] op_sel_hi:[1,0,1]
	v_pk_fma_f32 v[12:13], v[106:107], v[162:163], v[12:13] op_sel_hi:[1,0,1]
	s_waitcnt vmcnt(10)
	v_pk_fma_f32 v[2:3], v[112:113], v[58:59], v[2:3] op_sel_hi:[1,0,1]
	v_pk_fma_f32 v[0:1], v[110:111], v[58:59], v[0:1] op_sel_hi:[1,0,1]
	v_pk_fma_f32 v[6:7], v[112:113], v[58:59], v[6:7] op_sel:[0,1,0]
	v_pk_fma_f32 v[4:5], v[110:111], v[58:59], v[4:5] op_sel:[0,1,0]
	v_pk_fma_f32 v[10:11], v[112:113], v[60:61], v[10:11] op_sel_hi:[1,0,1]
	v_pk_fma_f32 v[8:9], v[110:111], v[60:61], v[8:9] op_sel_hi:[1,0,1]
	v_pk_fma_f32 v[14:15], v[112:113], v[164:165], v[14:15] op_sel_hi:[1,0,1]
	v_pk_fma_f32 v[12:13], v[110:111], v[164:165], v[12:13] op_sel_hi:[1,0,1]
	s_waitcnt vmcnt(9)
	v_pk_fma_f32 v[2:3], v[116:117], v[62:63], v[2:3] op_sel_hi:[1,0,1]
	v_pk_fma_f32 v[0:1], v[114:115], v[62:63], v[0:1] op_sel_hi:[1,0,1]
	v_pk_fma_f32 v[6:7], v[116:117], v[62:63], v[6:7] op_sel:[0,1,0]
	v_pk_fma_f32 v[4:5], v[114:115], v[62:63], v[4:5] op_sel:[0,1,0]
	v_pk_fma_f32 v[10:11], v[116:117], v[64:65], v[10:11] op_sel_hi:[1,0,1]
	v_pk_fma_f32 v[8:9], v[114:115], v[64:65], v[8:9] op_sel_hi:[1,0,1]
	v_pk_fma_f32 v[14:15], v[116:117], v[166:167], v[14:15] op_sel_hi:[1,0,1]
	v_pk_fma_f32 v[12:13], v[114:115], v[166:167], v[12:13] op_sel_hi:[1,0,1]
	s_waitcnt vmcnt(8)
	v_pk_fma_f32 v[2:3], v[120:121], v[66:67], v[2:3] op_sel_hi:[1,0,1]
	v_pk_fma_f32 v[0:1], v[118:119], v[66:67], v[0:1] op_sel_hi:[1,0,1]
	v_pk_fma_f32 v[6:7], v[120:121], v[66:67], v[6:7] op_sel:[0,1,0]
	v_pk_fma_f32 v[4:5], v[118:119], v[66:67], v[4:5] op_sel:[0,1,0]
	v_pk_fma_f32 v[10:11], v[120:121], v[68:69], v[10:11] op_sel_hi:[1,0,1]
	v_pk_fma_f32 v[8:9], v[118:119], v[68:69], v[8:9] op_sel_hi:[1,0,1]
	v_pk_fma_f32 v[14:15], v[120:121], v[168:169], v[14:15] op_sel_hi:[1,0,1]
	v_pk_fma_f32 v[12:13], v[118:119], v[168:169], v[12:13] op_sel_hi:[1,0,1]
	s_waitcnt vmcnt(7)
	v_pk_fma_f32 v[2:3], v[124:125], v[70:71], v[2:3] op_sel_hi:[1,0,1]
	v_pk_fma_f32 v[0:1], v[122:123], v[70:71], v[0:1] op_sel_hi:[1,0,1]
	v_pk_fma_f32 v[6:7], v[124:125], v[70:71], v[6:7] op_sel:[0,1,0]
	v_pk_fma_f32 v[4:5], v[122:123], v[70:71], v[4:5] op_sel:[0,1,0]
	v_pk_fma_f32 v[10:11], v[124:125], v[72:73], v[10:11] op_sel_hi:[1,0,1]
	v_pk_fma_f32 v[8:9], v[122:123], v[72:73], v[8:9] op_sel_hi:[1,0,1]
	v_pk_fma_f32 v[14:15], v[124:125], v[170:171], v[14:15] op_sel_hi:[1,0,1]
	v_pk_fma_f32 v[12:13], v[122:123], v[170:171], v[12:13] op_sel_hi:[1,0,1]
	s_waitcnt vmcnt(6)
	v_pk_fma_f32 v[2:3], v[128:129], v[74:75], v[2:3] op_sel_hi:[1,0,1]
	v_pk_fma_f32 v[0:1], v[126:127], v[74:75], v[0:1] op_sel_hi:[1,0,1]
	v_pk_fma_f32 v[6:7], v[128:129], v[74:75], v[6:7] op_sel:[0,1,0]
	v_pk_fma_f32 v[4:5], v[126:127], v[74:75], v[4:5] op_sel:[0,1,0]
	v_pk_fma_f32 v[10:11], v[128:129], v[76:77], v[10:11] op_sel_hi:[1,0,1]
	v_pk_fma_f32 v[8:9], v[126:127], v[76:77], v[8:9] op_sel_hi:[1,0,1]
	v_pk_fma_f32 v[14:15], v[128:129], v[172:173], v[14:15] op_sel_hi:[1,0,1]
	v_pk_fma_f32 v[12:13], v[126:127], v[172:173], v[12:13] op_sel_hi:[1,0,1]
	s_waitcnt vmcnt(5)
	v_pk_fma_f32 v[2:3], v[132:133], v[78:79], v[2:3] op_sel_hi:[1,0,1]
	v_pk_fma_f32 v[0:1], v[130:131], v[78:79], v[0:1] op_sel_hi:[1,0,1]
	v_pk_fma_f32 v[6:7], v[132:133], v[78:79], v[6:7] op_sel:[0,1,0]
	v_pk_fma_f32 v[4:5], v[130:131], v[78:79], v[4:5] op_sel:[0,1,0]
	v_pk_fma_f32 v[10:11], v[132:133], v[80:81], v[10:11] op_sel_hi:[1,0,1]
	v_pk_fma_f32 v[8:9], v[130:131], v[80:81], v[8:9] op_sel_hi:[1,0,1]
	v_pk_fma_f32 v[14:15], v[132:133], v[174:175], v[14:15] op_sel_hi:[1,0,1]
	v_pk_fma_f32 v[12:13], v[130:131], v[174:175], v[12:13] op_sel_hi:[1,0,1]
	s_waitcnt vmcnt(4)
	v_pk_fma_f32 v[2:3], v[136:137], v[82:83], v[2:3] op_sel_hi:[1,0,1]
	v_pk_fma_f32 v[0:1], v[134:135], v[82:83], v[0:1] op_sel_hi:[1,0,1]
	v_pk_fma_f32 v[6:7], v[136:137], v[82:83], v[6:7] op_sel:[0,1,0]
	v_pk_fma_f32 v[4:5], v[134:135], v[82:83], v[4:5] op_sel:[0,1,0]
	v_pk_fma_f32 v[10:11], v[136:137], v[84:85], v[10:11] op_sel_hi:[1,0,1]
	v_pk_fma_f32 v[8:9], v[134:135], v[84:85], v[8:9] op_sel_hi:[1,0,1]
	v_pk_fma_f32 v[14:15], v[136:137], v[176:177], v[14:15] op_sel_hi:[1,0,1]
	v_pk_fma_f32 v[12:13], v[134:135], v[176:177], v[12:13] op_sel_hi:[1,0,1]
	s_waitcnt vmcnt(3)
	v_pk_fma_f32 v[2:3], v[140:141], v[86:87], v[2:3] op_sel_hi:[1,0,1]
	v_pk_fma_f32 v[0:1], v[138:139], v[86:87], v[0:1] op_sel_hi:[1,0,1]
	v_pk_fma_f32 v[6:7], v[140:141], v[86:87], v[6:7] op_sel:[0,1,0]
	v_pk_fma_f32 v[4:5], v[138:139], v[86:87], v[4:5] op_sel:[0,1,0]
	v_pk_fma_f32 v[10:11], v[140:141], v[88:89], v[10:11] op_sel_hi:[1,0,1]
	v_pk_fma_f32 v[8:9], v[138:139], v[88:89], v[8:9] op_sel_hi:[1,0,1]
	v_pk_fma_f32 v[14:15], v[140:141], v[178:179], v[14:15] op_sel_hi:[1,0,1]
	v_pk_fma_f32 v[12:13], v[138:139], v[178:179], v[12:13] op_sel_hi:[1,0,1]
	s_waitcnt vmcnt(2)
	v_pk_fma_f32 v[2:3], v[144:145], v[90:91], v[2:3] op_sel_hi:[1,0,1]
	v_pk_fma_f32 v[0:1], v[142:143], v[90:91], v[0:1] op_sel_hi:[1,0,1]
	v_pk_fma_f32 v[6:7], v[144:145], v[90:91], v[6:7] op_sel:[0,1,0]
	v_pk_fma_f32 v[4:5], v[142:143], v[90:91], v[4:5] op_sel:[0,1,0]
	v_pk_fma_f32 v[10:11], v[144:145], v[92:93], v[10:11] op_sel_hi:[1,0,1]
	v_pk_fma_f32 v[8:9], v[142:143], v[92:93], v[8:9] op_sel_hi:[1,0,1]
	v_pk_fma_f32 v[14:15], v[144:145], v[180:181], v[14:15] op_sel_hi:[1,0,1]
	v_pk_fma_f32 v[12:13], v[142:143], v[180:181], v[12:13] op_sel_hi:[1,0,1]
	s_waitcnt vmcnt(1)
	v_pk_fma_f32 v[2:3], v[148:149], v[94:95], v[2:3] op_sel_hi:[1,0,1]
	v_pk_fma_f32 v[0:1], v[146:147], v[94:95], v[0:1] op_sel_hi:[1,0,1]
	v_pk_fma_f32 v[6:7], v[148:149], v[94:95], v[6:7] op_sel:[0,1,0]
	v_pk_fma_f32 v[4:5], v[146:147], v[94:95], v[4:5] op_sel:[0,1,0]
	v_pk_fma_f32 v[10:11], v[148:149], v[96:97], v[10:11] op_sel_hi:[1,0,1]
	v_pk_fma_f32 v[8:9], v[146:147], v[96:97], v[8:9] op_sel_hi:[1,0,1]
	v_pk_fma_f32 v[14:15], v[148:149], v[182:183], v[14:15] op_sel_hi:[1,0,1]
	v_pk_fma_f32 v[12:13], v[146:147], v[182:183], v[12:13] op_sel_hi:[1,0,1]
	s_waitcnt vmcnt(0)
	v_pk_fma_f32 v[2:3], v[152:153], v[98:99], v[2:3] op_sel_hi:[1,0,1]
	v_pk_fma_f32 v[0:1], v[150:151], v[98:99], v[0:1] op_sel_hi:[1,0,1]
	v_pk_fma_f32 v[6:7], v[152:153], v[98:99], v[6:7] op_sel:[0,1,0]
	v_pk_fma_f32 v[4:5], v[150:151], v[98:99], v[4:5] op_sel:[0,1,0]
	v_pk_fma_f32 v[10:11], v[152:153], v[100:101], v[10:11] op_sel_hi:[1,0,1]
	v_pk_fma_f32 v[8:9], v[150:151], v[100:101], v[8:9] op_sel_hi:[1,0,1]
	v_pk_fma_f32 v[14:15], v[152:153], v[184:185], v[14:15] op_sel_hi:[1,0,1]
	v_pk_fma_f32 v[12:13], v[150:151], v[184:185], v[12:13] op_sel_hi:[1,0,1]
	s_cbranch_scc0 .LBB0_42
	ds_write_b128 v28, v[0:3] offset:40960
	ds_write_b128 v28, v[4:7] offset:41984
	ds_write_b128 v28, v[8:11] offset:43008
	ds_write_b128 v28, v[12:15] offset:44032
	s_waitcnt lgkmcnt(0)
	s_barrier
	s_and_saveexec_b64 s[8:9], s[4:5]
	s_cbranch_execz .LBB0_35
	v_or_b32_sdwa v0, s21, v20 dst_sel:DWORD dst_unused:UNUSED_PAD src0_sel:DWORD src1_sel:BYTE_0
	v_ashrrev_i32_e32 v1, 31, v0
	v_or_b32_sdwa v2, s17, v20 dst_sel:DWORD dst_unused:UNUSED_PAD src0_sel:DWORD src1_sel:BYTE_0
	v_lshl_add_u64 v[0:1], v[0:1], 2, s[10:11]
	v_add_u32_e32 v2, s21, v2
	s_mov_b64 s[10:11], 0
	v_mov_b32_e32 v3, v29
	v_mov_b32_e32 v4, v20

.LBB0_63:
	s_lshr_b32 s14, s4, 7
	v_cvt_f32_u32_e32 v0, s14
	s_sub_i32 s37, 0, s14
	s_abs_i32 s16, s17
	s_ashr_i32 s15, s17, 31
	v_rcp_iflag_f32_e32 v0, v0
	s_nop 0
	v_mul_f32_e32 v0, 0x4f7ffffe, v0
	v_cvt_u32_f32_e32 v0, v0
	s_nop 0
	v_readfirstlane_b32 s38, v0
	s_mul_i32 s37, s37, s38
	s_mul_hi_u32 s37, s38, s37
	s_add_i32 s38, s38, s37
	s_mul_hi_u32 s37, s16, s38
	s_mul_i32 s38, s37, s14
	s_sub_i32 s16, s16, s38
	s_add_i32 s39, s37, 1
	s_sub_i32 s38, s16, s14
	s_cmp_ge_u32 s16, s14
	s_cselect_b32 s37, s39, s37
	s_cselect_b32 s16, s38, s16
	s_add_i32 s38, s37, 1
	s_cmp_ge_u32 s16, s14
	s_cselect_b32 s16, s38, s37
	s_xor_b32 s16, s16, s15
	s_sub_i32 s15, s16, s15
	s_mul_i32 s16, s15, s14
	s_lshl_b32 s14, s15, 6
	v_or_b32_e32 v0, s14, v60
	s_ashr_i32 s15, s14, 31
	s_sub_i32 s16, s17, s16
	s_mul_i32 s17, s15, s4
	v_mad_u64_u32 v[0:1], s[38:39], v0, s4, 0
	s_lshl_b32 s16, s16, 7
	v_add_u32_e32 v1, s17, v1
	s_waitcnt lgkmcnt(0)
	v_lshl_add_u64 v[0:1], v[0:1], 2, s[18:19]
	s_ashr_i32 s17, s16, 31
	v_lshl_add_u64 v[0:1], s[16:17], 2, v[0:1]
	v_lshl_add_u64 v[4:5], v[0:1], 0, v[56:57]
	s_lshl_b64 s[18:19], s[4:5], 3
	v_lshl_add_u64 v[8:9], v[4:5], 0, s[18:19]
	global_load_dwordx4 v[0:3], v[4:5], off nt
	v_lshl_add_u64 v[12:13], v[8:9], 0, s[18:19]
	global_load_dwordx4 v[4:7], v[8:9], off nt
	s_mul_i32 s4, s12, s17
	global_load_dwordx4 v[8:11], v[12:13], off nt
	v_lshl_add_u64 v[12:13], v[12:13], 0, s[18:19]
	global_load_dwordx4 v[20:23], v[12:13], off nt
	v_lshl_add_u64 v[12:13], v[12:13], 0, s[18:19]
	v_lshl_add_u64 v[14:15], v[12:13], 0, s[18:19]
	global_load_dwordx4 v[40:43], v[12:13], off nt
	global_load_dwordx4 v[48:51], v[14:15], off nt
	v_lshl_add_u64 v[12:13], v[14:15], 0, s[18:19]
	v_lshl_add_u64 v[14:15], v[12:13], 0, s[18:19]
	global_load_dwordx4 v[66:69], v[12:13], off nt
	global_load_dwordx4 v[70:73], v[14:15], off nt
	v_lshl_add_u64 v[12:13], v[14:15], 0, s[18:19]
	global_load_dwordx4 v[74:77], v[12:13], off nt
	v_lshl_add_u64 v[12:13], v[12:13], 0, s[18:19]
	global_load_dwordx4 v[78:81], v[12:13], off nt
	v_lshl_add_u64 v[12:13], v[12:13], 0, s[18:19]
	global_load_dwordx4 v[82:85], v[12:13], off nt
	v_lshl_add_u64 v[12:13], v[12:13], 0, s[18:19]
	global_load_dwordx4 v[86:89], v[12:13], off nt
	v_lshl_add_u64 v[12:13], v[12:13], 0, s[18:19]
	global_load_dwordx4 v[90:93], v[12:13], off nt
	v_lshl_add_u64 v[12:13], v[12:13], 0, s[18:19]
	global_load_dwordx4 v[94:97], v[12:13], off nt
	v_lshl_add_u64 v[14:15], v[12:13], 0, s[18:19]
	global_load_dwordx4 v[98:101], v[14:15], off nt
	v_lshl_add_u64 v[12:13], v[14:15], 0, s[18:19]
	global_load_dwordx4 v[102:105], v[12:13], off nt
	v_lshl_add_u64 v[14:15], v[12:13], 0, s[18:19]
	global_load_dwordx4 v[106:109], v[14:15], off nt
	v_lshl_add_u64 v[12:13], v[14:15], 0, s[18:19]
	global_load_dwordx4 v[110:113], v[12:13], off nt
	v_lshl_add_u64 v[14:15], v[12:13], 0, s[18:19]
	global_load_dwordx4 v[114:117], v[14:15], off nt
	v_lshl_add_u64 v[12:13], v[14:15], 0, s[18:19]
	global_load_dwordx4 v[118:121], v[12:13], off nt
	v_lshl_add_u64 v[14:15], v[12:13], 0, s[18:19]
	global_load_dwordx4 v[122:125], v[14:15], off nt
	v_lshl_add_u64 v[12:13], v[14:15], 0, s[18:19]
	global_load_dwordx4 v[126:129], v[12:13], off nt
	v_lshl_add_u64 v[14:15], v[12:13], 0, s[18:19]
	global_load_dwordx4 v[130:133], v[14:15], off nt
	v_lshl_add_u64 v[12:13], v[14:15], 0, s[18:19]
	global_load_dwordx4 v[134:137], v[12:13], off nt
	v_lshl_add_u64 v[14:15], v[12:13], 0, s[18:19]
	v_lshl_add_u64 v[12:13], v[14:15], 0, s[18:19]
	global_load_dwordx4 v[138:141], v[14:15], off nt
	v_lshl_add_u64 v[14:15], v[12:13], 0, s[18:19]
	global_load_dwordx4 v[52:55], v[12:13], off nt
	v_lshl_add_u64 v[12:13], v[14:15], 0, s[18:19]
	global_load_dwordx4 v[44:47], v[14:15], off nt
	v_lshl_add_u64 v[14:15], v[12:13], 0, s[18:19]
	global_load_dwordx4 v[36:39], v[12:13], off nt
	v_lshl_add_u64 v[12:13], v[14:15], 0, s[18:19]
	global_load_dwordx4 v[32:35], v[14:15], off nt
	v_lshl_add_u64 v[14:15], v[12:13], 0, s[18:19]
	global_load_dwordx4 v[28:31], v[12:13], off nt
	v_lshl_add_u64 v[12:13], v[14:15], 0, s[18:19]
	global_load_dwordx4 v[16:19], v[14:15], off nt
	s_nop 0
	global_load_dwordx4 v[12:15], v[12:13], off nt
	s_add_i32 s36, s36, 1
	s_add_i32 s2, s2, s3
	s_waitcnt vmcnt(31)
	v_permlane32_swap_b32_e32 v0, v1
	v_permlane32_swap_b32_e32 v2, v3
	v_cvt_pk_bf16_f32 v24, v0, v1
	v_cvt_pk_bf16_f32 v0, v2, v3
	s_waitcnt vmcnt(29)
	v_mov_b32_e32 v2, v9
	s_nop 1
	v_permlane32_swap_b32_e32 v8, v2
	v_permlane32_swap_b32_e32 v4, v5
	v_permlane32_swap_b32_e32 v6, v7
	v_cvt_pk_bf16_f32 v25, v4, v5
	v_cvt_pk_bf16_f32 v1, v6, v7
	v_cvt_pk_bf16_f32 v26, v8, v2
	v_mov_b32_e32 v2, v11
	s_waitcnt vmcnt(28)
	v_mov_b32_e32 v3, v21
	v_permlane32_swap_b32_e32 v10, v2
	s_nop 0
	v_permlane32_swap_b32_e32 v20, v3
	v_cvt_pk_bf16_f32 v2, v10, v2
	v_cvt_pk_bf16_f32 v27, v20, v3
	v_mov_b32_e32 v3, v23
	s_waitcnt vmcnt(27)
	v_mov_b32_e32 v4, v41
	v_mov_b32_e32 v5, v43
	v_permlane32_swap_b32_e32 v22, v3
	v_permlane32_swap_b32_e32 v40, v4
	v_permlane32_swap_b32_e32 v42, v5
	v_cvt_pk_bf16_f32 v3, v22, v3
	v_cvt_pk_bf16_f32 v40, v40, v4
	v_cvt_pk_bf16_f32 v4, v42, v5
	s_waitcnt vmcnt(26)
	v_mov_b32_e32 v5, v49
	s_nop 1
	v_permlane32_swap_b32_e32 v48, v5
	v_cvt_pk_bf16_f32 v41, v48, v5
	v_mov_b32_e32 v5, v51
	s_waitcnt vmcnt(25)
	v_mov_b32_e32 v6, v67
	v_permlane32_swap_b32_e32 v50, v5
	s_nop 0
	v_permlane32_swap_b32_e32 v66, v6
	v_cvt_pk_bf16_f32 v5, v50, v5
	v_cvt_pk_bf16_f32 v42, v66, v6
	v_mov_b32_e32 v6, v69
	s_waitcnt vmcnt(24)
	v_mov_b32_e32 v7, v71
	v_permlane32_swap_b32_e32 v68, v6
	s_nop 0
	v_permlane32_swap_b32_e32 v70, v7
	v_cvt_pk_bf16_f32 v6, v68, v6
	v_cvt_pk_bf16_f32 v43, v70, v7
	v_mov_b32_e32 v7, v73
	s_waitcnt vmcnt(23)
	v_mov_b32_e32 v8, v75
	v_mov_b32_e32 v9, v77
	v_permlane32_swap_b32_e32 v72, v7
	v_permlane32_swap_b32_e32 v74, v8
	v_permlane32_swap_b32_e32 v76, v9
	v_cvt_pk_bf16_f32 v7, v72, v7
	v_cvt_pk_bf16_f32 v66, v74, v8
	v_cvt_pk_bf16_f32 v8, v76, v9
	s_waitcnt vmcnt(22)
	v_mov_b32_e32 v9, v79
	s_nop 1
	v_permlane32_swap_b32_e32 v78, v9
	v_cvt_pk_bf16_f32 v67, v78, v9
	v_mov_b32_e32 v9, v81
	s_waitcnt vmcnt(21)
	v_mov_b32_e32 v10, v83
	v_permlane32_swap_b32_e32 v80, v9
	s_nop 0
	v_permlane32_swap_b32_e32 v82, v10
	v_cvt_pk_bf16_f32 v9, v80, v9
	v_cvt_pk_bf16_f32 v68, v82, v10
	v_mov_b32_e32 v10, v85
	s_waitcnt vmcnt(20)
	v_mov_b32_e32 v11, v87
	v_permlane32_swap_b32_e32 v84, v10
	s_nop 0
	v_permlane32_swap_b32_e32 v86, v11
	v_cvt_pk_bf16_f32 v10, v84, v10
	v_cvt_pk_bf16_f32 v69, v86, v11
	v_mov_b32_e32 v11, v89
	s_waitcnt vmcnt(19)
	v_mov_b32_e32 v20, v91
	v_mov_b32_e32 v21, v93
	v_permlane32_swap_b32_e32 v88, v11
	v_permlane32_swap_b32_e32 v90, v20
	v_permlane32_swap_b32_e32 v92, v21
	v_cvt_pk_bf16_f32 v11, v88, v11
	v_cvt_pk_bf16_f32 v70, v90, v20
	v_cvt_pk_bf16_f32 v20, v92, v21
	s_waitcnt vmcnt(18)
	v_mov_b32_e32 v21, v95
	s_nop 1
	v_permlane32_swap_b32_e32 v94, v21
	v_cvt_pk_bf16_f32 v71, v94, v21
	v_mov_b32_e32 v21, v97
	s_waitcnt vmcnt(17)
	v_mov_b32_e32 v22, v99
	v_permlane32_swap_b32_e32 v96, v21
	s_nop 0
	v_permlane32_swap_b32_e32 v98, v22
	v_cvt_pk_bf16_f32 v21, v96, v21
	v_cvt_pk_bf16_f32 v72, v98, v22
	v_mov_b32_e32 v22, v101
	s_waitcnt vmcnt(16)
	v_mov_b32_e32 v23, v103
	v_permlane32_swap_b32_e32 v100, v22
	s_nop 0
	v_permlane32_swap_b32_e32 v102, v23
	v_cvt_pk_bf16_f32 v22, v100, v22
	v_cvt_pk_bf16_f32 v73, v102, v23
	v_mov_b32_e32 v23, v105
	s_waitcnt vmcnt(15)
	v_mov_b32_e32 v48, v107
	v_mov_b32_e32 v49, v109
	v_permlane32_swap_b32_e32 v104, v23
	v_permlane32_swap_b32_e32 v106, v48
	v_permlane32_swap_b32_e32 v108, v49
	v_cvt_pk_bf16_f32 v23, v104, v23
	v_cvt_pk_bf16_f32 v74, v106, v48
	v_cvt_pk_bf16_f32 v48, v108, v49
	s_waitcnt vmcnt(14)
	v_mov_b32_e32 v49, v111
	s_nop 1
	v_permlane32_swap_b32_e32 v110, v49
	v_cvt_pk_bf16_f32 v75, v110, v49
	v_mov_b32_e32 v49, v113
	s_waitcnt vmcnt(13)
	v_mov_b32_e32 v50, v115
	v_permlane32_swap_b32_e32 v112, v49
	s_nop 0
	v_permlane32_swap_b32_e32 v114, v50
	v_cvt_pk_bf16_f32 v49, v112, v49
	v_cvt_pk_bf16_f32 v76, v114, v50
	v_mov_b32_e32 v50, v117
	s_waitcnt vmcnt(12)
	v_mov_b32_e32 v51, v119
	v_permlane32_swap_b32_e32 v116, v50
	s_nop 0
	v_permlane32_swap_b32_e32 v118, v51
	v_cvt_pk_bf16_f32 v50, v116, v50
	v_cvt_pk_bf16_f32 v77, v118, v51
	v_mov_b32_e32 v51, v121
	s_waitcnt vmcnt(11)
	v_mov_b32_e32 v65, v123
	v_permlane32_swap_b32_e32 v120, v51
	s_nop 0
	v_permlane32_swap_b32_e32 v122, v65
	v_cvt_pk_bf16_f32 v51, v120, v51
	v_mov_b32_e32 v79, v125
	v_cvt_pk_bf16_f32 v78, v122, v65
	s_waitcnt vmcnt(10)
	v_mov_b32_e32 v65, v127
	v_permlane32_swap_b32_e32 v124, v79
	s_nop 0
	v_permlane32_swap_b32_e32 v126, v65
	v_cvt_pk_bf16_f32 v82, v124, v79
	v_cvt_pk_bf16_f32 v79, v126, v65
	v_mov_b32_e32 v65, v129
	s_nop 1
	v_permlane32_swap_b32_e32 v128, v65
	v_cvt_pk_bf16_f32 v83, v128, v65
	s_waitcnt vmcnt(9)
	v_mov_b32_e32 v65, v131
	s_nop 1
	v_permlane32_swap_b32_e32 v130, v65
	v_cvt_pk_bf16_f32 v80, v130, v65
	v_mov_b32_e32 v65, v133
	s_nop 1
	v_permlane32_swap_b32_e32 v132, v65
	v_cvt_pk_bf16_f32 v84, v132, v65
	s_waitcnt vmcnt(8)
	v_mov_b32_e32 v65, v135
	s_nop 1
	v_permlane32_swap_b32_e32 v134, v65
	v_cvt_pk_bf16_f32 v81, v134, v65
	v_mov_b32_e32 v65, v137
	s_nop 1
	v_permlane32_swap_b32_e32 v136, v65
	s_waitcnt vmcnt(7)
	v_mov_b32_e32 v87, v141
	v_cvt_pk_bf16_f32 v85, v136, v65
	v_mov_b32_e32 v65, v139
	s_nop 0
	v_permlane32_swap_b32_e32 v140, v87
	s_waitcnt vmcnt(6)
	v_permlane32_swap_b32_e32 v52, v53
	v_permlane32_swap_b32_e32 v138, v65
	v_cvt_pk_bf16_f32 v86, v138, v65
	v_cvt_pk_bf16_f32 v90, v140, v87
	v_cvt_pk_bf16_f32 v87, v52, v53
	v_mov_b32_e32 v52, v55
	s_waitcnt vmcnt(5)
	v_permlane32_swap_b32_e32 v44, v45
	v_permlane32_swap_b32_e32 v54, v52
	v_cvt_pk_bf16_f32 v91, v54, v52
	v_cvt_pk_bf16_f32 v88, v44, v45
	v_mov_b32_e32 v44, v47
	s_waitcnt vmcnt(4)
	v_permlane32_swap_b32_e32 v36, v37
	v_permlane32_swap_b32_e32 v46, v44
	v_cvt_pk_bf16_f32 v92, v46, v44
	v_cvt_pk_bf16_f32 v89, v36, v37
	v_mov_b32_e32 v36, v39
	s_nop 1
	v_permlane32_swap_b32_e32 v38, v36
	s_waitcnt vmcnt(3)
	v_permlane32_swap_b32_e32 v32, v33
	s_waitcnt vmcnt(2)
	v_permlane32_swap_b32_e32 v28, v29
	v_cvt_pk_bf16_f32 v93, v38, v36
	v_permlane32_swap_b32_e32 v34, v35
	v_cvt_pk_bf16_f32 v32, v32, v33
	v_cvt_pk_bf16_f32 v36, v34, v35
	v_cvt_pk_bf16_f32 v33, v28, v29
	v_mov_b32_e32 v28, v31
	s_waitcnt vmcnt(1)
	v_permlane32_swap_b32_e32 v16, v17
	v_permlane32_swap_b32_e32 v30, v28
	v_cvt_pk_bf16_f32 v37, v30, v28
	v_cvt_pk_bf16_f32 v34, v16, v17
	v_mov_b32_e32 v16, v19
	s_waitcnt vmcnt(0)
	v_permlane32_swap_b32_e32 v12, v13
	v_permlane32_swap_b32_e32 v18, v16
	v_cvt_pk_bf16_f32 v38, v18, v16
	v_cvt_pk_bf16_f32 v35, v12, v13
	v_mov_b32_e32 v12, v15
	s_nop 1
	v_permlane32_swap_b32_e32 v14, v12
	v_or_b32_e32 v30, s16, v61
	v_cvt_pk_bf16_f32 v39, v14, v12
	ds_write_b128 v62, v[24:27] offset:40960
	ds_write_b128 v62, v[40:43] offset:40976
	ds_write_b128 v62, v[66:69] offset:40992
	ds_write_b128 v62, v[70:73] offset:41008
	ds_write_b128 v62, v[74:77] offset:41024
	ds_write_b128 v62, v[78:81] offset:41040
	ds_write_b128 v62, v[86:89] offset:41056
	ds_write_b128 v62, v[32:35] offset:41072
	v_mul_lo_u32 v14, s13, v30
	v_mad_u64_u32 v[12:13], s[16:17], s12, v30, 0
	s_waitcnt lgkmcnt(0)
	v_add3_u32 v13, v13, s4, v14
	v_lshl_add_u64 v[16:17], v[12:13], 1, s[10:11]
	ds_read_b128 v[12:15], v63 offset:40960
	s_lshl_b64 s[16:17], s[14:15], 1
	v_lshl_add_u64 v[16:17], v[16:17], 0, s[16:17]
	v_lshl_add_u64 v[24:25], v[16:17], 0, v[58:59]
	ds_read_b128 v[16:19], v63 offset:42112
	s_waitcnt lgkmcnt(1)
	global_store_dwordx4 v[24:25], v[12:15], off sc1
	s_lshl_b64 s[14:15], s[12:13], 6
	ds_read_b128 v[12:15], v63 offset:43264
	v_lshl_add_u64 v[28:29], v[24:25], 0, s[14:15]
	ds_read_b128 v[24:27], v63 offset:44416
	s_waitcnt lgkmcnt(2)
	global_store_dwordx4 v[28:29], v[16:19], off sc1
	s_nop 1
	v_lshl_add_u64 v[16:17], v[28:29], 0, s[14:15]
	s_waitcnt lgkmcnt(1)
	global_store_dwordx4 v[16:17], v[12:15], off sc1
	v_lshl_add_u64 v[16:17], v[16:17], 0, s[14:15]
	ds_read_b128 v[12:15], v63 offset:45568
	s_waitcnt lgkmcnt(1)
	global_store_dwordx4 v[16:17], v[24:27], off sc1
	s_nop 1
	v_mad_u64_u32 v[24:25], s[18:19], s12, v64, v[16:17]
	s_mul_i32 s18, s13, 0xffffff42
	s_sub_i32 s37, s18, s12
	v_add_u32_e32 v25, s37, v25
	ds_read_b128 v[16:19], v63 offset:46720
	s_waitcnt lgkmcnt(1)
	global_store_dwordx4 v[24:25], v[12:15], off sc1
	ds_read_b128 v[12:15], v63 offset:47872
	v_lshl_add_u64 v[28:29], v[24:25], 0, s[14:15]
	ds_read_b128 v[24:27], v63 offset:49024
	s_waitcnt lgkmcnt(2)
	global_store_dwordx4 v[28:29], v[16:19], off sc1
	s_cmp_lg_u32 s1, s36
	s_nop 0
	v_lshl_add_u64 v[16:17], v[28:29], 0, s[14:15]
	s_waitcnt lgkmcnt(1)
	global_store_dwordx4 v[16:17], v[12:15], off sc1
	s_nop 1
	v_lshl_add_u64 v[12:13], v[16:17], 0, s[14:15]
	s_waitcnt lgkmcnt(0)
	global_store_dwordx4 v[12:13], v[24:27], off sc1
	s_waitcnt lgkmcnt(0)
	ds_write_b128 v62, v[0:3] offset:40960
	ds_write_b128 v62, v[4:7] offset:40976
	ds_write_b128 v62, v[8:11] offset:40992
	ds_write_b128 v62, v[20:23] offset:41008
	ds_write_b128 v62, v[48:51] offset:41024
	ds_write_b128 v62, v[82:85] offset:41040
	ds_write_b128 v62, v[90:93] offset:41056
	ds_write_b128 v62, v[36:39] offset:41072
	v_or_b32_e32 v0, 2, v30
	s_waitcnt lgkmcnt(0)
	v_mul_lo_u32 v1, s13, v0
	v_mad_u64_u32 v[4:5], s[18:19], s12, v0, 0
	v_add3_u32 v5, v5, s4, v1
	ds_read_b128 v[0:3], v63 offset:40960
	v_lshl_add_u64 v[4:5], v[4:5], 1, s[10:11]
	v_lshl_add_u64 v[4:5], v[4:5], 0, s[16:17]
	v_lshl_add_u64 v[8:9], v[4:5], 0, v[58:59]
	ds_read_b128 v[4:7], v63 offset:42112
	s_waitcnt lgkmcnt(1)
	global_store_dwordx4 v[8:9], v[0:3], off sc1
	ds_read_b128 v[0:3], v63 offset:43264
	v_lshl_add_u64 v[12:13], v[8:9], 0, s[14:15]
	ds_read_b128 v[8:11], v63 offset:44416
	s_waitcnt lgkmcnt(2)
	global_store_dwordx4 v[12:13], v[4:7], off sc1
	s_nop 1
	v_lshl_add_u64 v[4:5], v[12:13], 0, s[14:15]
	s_waitcnt lgkmcnt(1)
	global_store_dwordx4 v[4:5], v[0:3], off sc1
	ds_read_b128 v[0:3], v63 offset:45568
	v_lshl_add_u64 v[4:5], v[4:5], 0, s[14:15]
	s_waitcnt lgkmcnt(1)
	global_store_dwordx4 v[4:5], v[8:11], off sc1
	s_nop 1
	v_mad_u64_u32 v[8:9], s[10:11], s12, v64, v[4:5]
	v_add_u32_e32 v9, s37, v9
	ds_read_b128 v[4:7], v63 offset:46720
	s_waitcnt lgkmcnt(1)
	global_store_dwordx4 v[8:9], v[0:3], off sc1
	ds_read_b128 v[0:3], v63 offset:47872
	v_lshl_add_u64 v[12:13], v[8:9], 0, s[14:15]
	ds_read_b128 v[8:11], v63 offset:49024
	s_waitcnt lgkmcnt(2)
	global_store_dwordx4 v[12:13], v[4:7], off sc1
	s_nop 1
	v_lshl_add_u64 v[4:5], v[12:13], 0, s[14:15]
	s_waitcnt lgkmcnt(1)
	global_store_dwordx4 v[4:5], v[0:3], off sc1
	s_nop 1
	v_lshl_add_u64 v[0:1], v[4:5], 0, s[14:15]
	s_waitcnt lgkmcnt(0)
	global_store_dwordx4 v[0:1], v[8:11], off sc1
	s_waitcnt lgkmcnt(0)
	s_cbranch_scc0 .LBB0_93
